# power shaping: s_sleep 3 in MLA attention KV loop (non-critical side of MIX) on top of vt_pair2
# baseline (speedup 1.0000x reference)
; #define LBAR() asm volatile("s_waitcnt lgkmcnt(0)\n\ts_barrier" ::: "memory")
; template <int DQK, int DV, bool CAUSAL, bool MLA> ...
;     ...
;     for (int kt = 0; kt < nkt; ++kt) {
;         LBAR();
; #pragma unroll
;         for (int i = 0; i < NKC; ++i) { const int idx = tid + 512 * i; if (idx < 64 * KCH) { const int key = idx / KCH, ch = idx % KCH; *(u32x4*)(Ks + key * KS + ch * 16) = kreg[i]; } }
; #pragma unroll
;         for (int i = 0; i < NVC; ++i) { const int idx = tid + 512 * i; const int dv = idx >> 3, ch = idx & 7; *(u32x4*)(Vs + dv * VS + ch * 16) = vreg[i]; }
.LBB0_1432:
	s_sleep 3
	s_waitcnt lgkmcnt(0)
	s_barrier
	s_and_saveexec_b64 s[4:5], vcc
	s_cbranch_execz .LBB0_1434
	v_add_u32_e32 v40, v77, v78
	s_waitcnt vmcnt(1)
	ds_write_b128 v40, v[0:3]
